# A-attn: selection-word loads issued before the K/V tile loads (K/V stay in flight across the barrier); ph5/ph6 work queues split per XCD (unit = ticket*8 + xcc, steal when empty); indexer pass-0 loop
# speedup vs baseline: 1.0234x; 1.0057x over previous
; #define LAS __attribute__((address_space(3)))
; __device__ __forceinline__ int otid() { int t = __builtin_amdgcn_workitem_id_x(); asm volatile("" : "+v"(t)); return t; }
; __device__ __forceinline__ int next_unit(int* counter, LAS unsigned char* lds) {
;     LAS int* slot = (LAS int*)(lds + LDS_MISC);
;     if (otid() == 0) *slot = atomicAdd(counter, 1);
;     __syncthreads();
;     return __builtin_amdgcn_readfirstlane(*slot);
; }
; __global__ void __launch_bounds__(NTHREADS) mega_fwd(Params p) {
;     ...
;                     int* ctr = ctl + (l * 4 + ch) * 2 + 1;
;                     const int n_a = nbc * 8 * 32;
;                     for (;;) {
;                         int u = next_unit(ctr, lds);
;                         if (u >= n_a) break;
.LBB0_312:
	s_waitcnt lgkmcnt(0)
	v_mov_b32_e32 v0, v192
	s_nop 0
	v_cmp_eq_u32_e32 vcc, 0, v0
	s_and_saveexec_b64 s[0:1], vcc
	s_cbranch_execz .LBB0_316
	s_mov_b64 s[36:37], exec
	v_mbcnt_lo_u32_b32 v0, s36, 0
	v_mbcnt_hi_u32_b32 v0, s37, v0
	v_cmp_eq_u32_e32 vcc, 0, v0
	s_and_saveexec_b64 s[30:31], vcc
	s_cbranch_execz .LBB0_315
	s_getreg_b32 s36, hwreg(HW_REG_XCC_ID, 0, 4)
	s_and_b32 s36, s36, 7
	s_mov_b32 vcc_hi, 0
.Lmy_q6_try:
	s_add_i32 vcc_lo, s36, vcc_hi
	s_and_b32 vcc_lo, vcc_lo, 7
	v_readlane_b32 s12, v255, 12
	v_readlane_b32 s13, v255, 13
	s_lshl_b32 s37, vcc_lo, 3
	v_mov_b32_e32 v3, s37
	v_mov_b32_e32 v2, 1
	s_and_b32 s37, s12, 0xff8
	s_sub_u32 s12, s12, s37
	s_lshl_b32 s37, s37, 3
	s_add_u32 s12, s12, s37
	s_nop 0
	global_atomic_add v2, v3, v2, s[12:13] offset:516 sc0
	s_waitcnt vmcnt(0)
	v_readlane_b32 s12, v253, 52
	v_readfirstlane_b32 s37, v2
	s_lshr_b32 s13, s12, 3
	s_cmp_lt_u32 s37, s13
	s_cbranch_scc1 .Lmy_q6_got
	s_add_i32 vcc_hi, vcc_hi, 1
	s_cmp_lt_u32 vcc_hi, 8
	s_cbranch_scc1 .Lmy_q6_try
	s_mov_b32 s37, s12
	s_branch .Lmy_q6_done
.Lmy_q6_got:
	s_lshl_b32 s37, s37, 3
	s_or_b32 s37, s37, vcc_lo
.Lmy_q6_done:
	v_mov_b32_e32 v2, s37

; #define LAS __attribute__((address_space(3)))
; #define ATT_LOAD(kt) do { const long kb_ = (long)(kt) * 64; \
;         rk0 = *(const u32x4*)(a.k + (kb_ + kkey0) * a.k_rs + kpart0 * 8); \
;         if (DQK == 96 && tid < 256) rk1 = *(const u32x4*)(a.k + (kb_ + kkey1) * a.k_rs + kpart1 * 8); \
;         rv0 = *(const u32x2*)(a.v + (kb_ + 2 * vkp) * a.v_rs + vdg * 4); rv1 = *(const u32x2*)(a.v + (kb_ + 2 * vkp + 1) * a.v_rs + vdg * 4); } while (0)
; template <int DQK, int MODE>
; __device__ __forceinline__ void attn_unit(LAS unsigned char* lds, const AttnArgs& a, const unsigned char* lut) {
;     ...
;     for (int kt = kt_lo; kt <= kt_hi; ++kt) {
;         const int cur = (kt - kt_lo) & 1;
;         if (kt < kt_hi) ATT_STORE(cur ^ 1);
;         if (kt + 1 < kt_hi) ATT_LOAD(kt + 2);
;         const unsigned long long mwc0 = mwn0, mwc1 = mwn1;
;         if (MODE == 2 && kt < kt_hi) { mwn0 = a.mask[(long)qi * 128 + kt + 1]; mwn1 = a.mask[(long)(qi + 16) * 128 + kt + 1]; }
;         const LAS bf16_t* sK = (const LAS bf16_t*)(lds + cur * 24576); const LAS bf16_t* sVt = (const LAS bf16_t*)(lds + cur * 24576 + 14336);
.LBB0_335:
	s_xor_b32 s18, s19, 1
	s_mulk_i32 s18, 0x6000
	s_add_i32 s18, s18, 0
	v_lshlrev_b32_e32 v66, 1, v122
	v_add3_u32 v66, s18, v61, v66
	s_waitcnt vmcnt(2)
	ds_write_b128 v66, v[46:49]
	s_waitcnt vmcnt(1)
	v_and_b32_e32 v66, 0xffff, v124
	v_add3_u32 v67, s18, v156, v157
	v_lshrrev_b32_e32 v68, 16, v124
	s_waitcnt vmcnt(0)
	v_lshl_or_b32 v66, v126, 16, v66
	v_and_or_b32 v68, v126, s69, v68
	v_add_u32_e32 v69, 0x3800, v67
	ds_write2_b32 v69, v66, v68 offset1:36
	v_and_b32_e32 v66, 0xffff, v125
	v_lshl_or_b32 v66, v127, 16, v66
	ds_write_b32 v67, v66 offset:14624
	v_lshrrev_b32_e32 v66, 16, v125
	v_and_or_b32 v66, v127, s69, v66
	v_add3_u32 v67, s18, v158, v157
	ds_write_b32 v67, v66 offset:14336
	s_add_i32 s18, s17, 1
	s_cmp_ge_i32 s18, s12
	s_cbranch_scc1 .LBB0_333
.LBB0_336:
	v_lshl_add_u64 v[68:69], s[92:93], 0, v[130:131]
	v_lshl_add_u64 v[66:67], s[92:93], 0, v[128:129]
	global_load_dwordx2 v[140:141], v[68:69], off
	global_load_dwordx2 v[138:139], v[66:67], off
	v_lshl_add_u64 v[70:71], s[92:93], 0, v[132:133]
	v_add_co_u32_e32 v72, vcc, 0xcb2a000, v70
	v_lshl_add_u64 v[46:47], s[92:93], 0, v[134:135]
	v_addc_co_u32_e32 v73, vcc, 0, v71, vcc
	v_add_co_u32_e32 v70, vcc, 0xcb2f000, v70
	global_load_dwordx4 v[46:49], v[46:47], off
	s_nop 0
	global_load_dwordx2 v[124:125], v[72:73], off offset:2304
	v_addc_co_u32_e32 v71, vcc, 0, v71, vcc
	global_load_dwordx2 v[126:127], v[70:71], off offset:1280
	s_branch .LBB0_334
.LBB0_337:
	v_lshl_add_u64 v[68:69], s[92:93], 0, v[130:131]
	v_lshl_add_u64 v[66:67], s[92:93], 0, v[128:129]
	global_load_dwordx2 v[140:141], v[68:69], off
	global_load_dwordx2 v[138:139], v[66:67], off
	s_waitcnt vmcnt(0)
	s_cmp_gt_i32 s16, s13
	s_cbranch_scc1 .LBB0_342

; #define ATT_LOAD(kt) do { const long kb_ = (long)(kt) * 64; \
;         rk0 = *(const u32x4*)(a.k + (kb_ + kkey0) * a.k_rs + kpart0 * 8); \
;         if (DQK == 96 && tid < 256) rk1 = *(const u32x4*)(a.k + (kb_ + kkey1) * a.k_rs + kpart1 * 8); \
;         rv0 = *(const u32x2*)(a.v + (kb_ + 2 * vkp) * a.v_rs + vdg * 4); rv1 = *(const u32x2*)(a.v + (kb_ + 2 * vkp + 1) * a.v_rs + vdg * 4); } while (0)
; template <int DQK, int MODE>
; __device__ __forceinline__ void attn_unit(LAS unsigned char* lds, const AttnArgs& a, const unsigned char* lut) {
;     ...
;     for (int kt = kt_lo; kt <= kt_hi; ++kt) {
;         const int cur = (kt - kt_lo) & 1;
;         if (kt < kt_hi) ATT_STORE(cur ^ 1);
;         if (kt + 1 < kt_hi) ATT_LOAD(kt + 2);
;         const unsigned long long mwc0 = mwn0, mwc1 = mwn1;
;         if (MODE == 2 && kt < kt_hi) { mwn0 = a.mask[(long)qi * 128 + kt + 1]; mwn1 = a.mask[(long)(qi + 16) * 128 + kt + 1]; }
;     ...
;         __syncthreads();
.LBB0_342:
	s_add_i32 s14, s14, 1
	s_add_i32 s16, s16, 64
	s_addk_i32 s15, 0xff00
	v_lshl_add_u64 v[128:129], v[128:129], 0, 8
	v_lshl_add_u64 v[130:131], v[130:131], 0, 8
	v_lshl_add_u64 v[132:133], v[132:133], 0, s[26:27]
	v_lshl_add_u64 v[134:135], v[134:135], 0, s[26:27]
	s_cmp_eq_u32 s17, s12
	v_add_u32_e32 v123, 0xffffff00, v123
	s_waitcnt lgkmcnt(0)
	s_barrier
	s_cbranch_scc1 .LBB0_310
	s_waitcnt vmcnt(3)
	v_mov_b64_e32 v[62:63], v[140:141]
	v_mov_b64_e32 v[64:65], v[138:139]
	s_mov_b32 s17, s18
	s_branch .LBB0_331

; #define LAS __attribute__((address_space(3)))
; __device__ __forceinline__ int otid() { int t = __builtin_amdgcn_workitem_id_x(); asm volatile("" : "+v"(t)); return t; }
; __device__ __forceinline__ int next_unit(int* counter, LAS unsigned char* lds) {
;     LAS int* slot = (LAS int*)(lds + LDS_MISC);
;     if (otid() == 0) *slot = atomicAdd(counter, 1);
;     __syncthreads();
;     return __builtin_amdgcn_readfirstlane(*slot);
; }
; __global__ void __launch_bounds__(NTHREADS) mega_fwd(Params p) {
;     ...
;                     int* ctr = ctl + (l * 4 + ch) * 2;
;                     const int n_idx = nbc * 256, n_c = nbc * 8 * 32, n_b = 3 * nbc * 8 * 32, n_d = nbc * 8 * 32;
;                     const int n_all = n_idx + n_c + n_b + n_d;
;                     for (;;) {
;                         int u = next_unit(ctr, lds);
;                         if (u >= n_all) break;
.Lmy_q5_try:
	s_add_i32 vcc_lo, s36, vcc_hi
	s_and_b32 vcc_lo, vcc_lo, 7
	v_readlane_b32 s12, v255, 12
	v_readlane_b32 s13, v255, 13
	s_lshl_b32 s37, vcc_lo, 3
	v_mov_b32_e32 v3, s37
	v_mov_b32_e32 v2, 1
	s_and_b32 s37, s12, 0xff8
	s_sub_u32 s12, s12, s37
	s_lshl_b32 s37, s37, 3
	s_add_u32 s12, s12, s37
	s_nop 0
	global_atomic_add v2, v3, v2, s[12:13] offset:512 sc0
	s_waitcnt vmcnt(0)
	v_readlane_b32 s12, v251, 0
	s_nop 0
	s_mulk_i32 s12, 0x600
	v_readfirstlane_b32 s37, v2
	s_lshr_b32 s13, s12, 3
	s_cmp_lt_u32 s37, s13
	s_cbranch_scc1 .Lmy_q5_got
	s_add_i32 vcc_hi, vcc_hi, 1
	s_cmp_lt_u32 vcc_hi, 8
	s_cbranch_scc1 .Lmy_q5_try
	s_mov_b32 s37, s12
	s_branch .Lmy_q5_done

; __device__ __forceinline__ void idx_scores(const bf16x8 ikf, const bf16x8 (&iq)[2][8], const float (&iw)[2][8], const bf16x8 (&iql)[2][2], float (&sc)[2][4]) {
; #pragma unroll
;     for (int qt = 0; qt < 2; ++qt) {
;         f32x4 L = (f32x4){0.f, 0.f, 0.f, 0.f};
;         L = __builtin_amdgcn_mfma_f32_16x16x32_bf16(ikf, iql[qt][0], L, 0, 0, 0);
;         L = __builtin_amdgcn_mfma_f32_16x16x32_bf16(ikf, iql[qt][1], L, 0, 0, 0);
; #pragma unroll
;         for (int j = 0; j < 4; ++j) sc[qt][j] = L[j];
; #pragma unroll
;         for (int h = 0; h < 8; ++h) {
;             f32x4 a = (f32x4){0.f, 0.f, 0.f, 0.f};
;             a = __builtin_amdgcn_mfma_f32_16x16x32_bf16(ikf, iq[qt][h], a, 0, 0, 0);
; #pragma unroll
;             for (int j = 0; j < 4; ++j) sc[qt][j] = __builtin_fmaf(iw[qt][h], __builtin_fabsf(a[j]), sc[qt][j]);
;         }
;     }
; }
; __device__ __forceinline__ unsigned mono_key(float s) { const unsigned u = __float_as_uint(s + 0.0f); return u ^ ((unsigned)((int)u >> 31) | 0x80000000u); }
; __device__ __forceinline__ bool indexer_fast(LAS unsigned char* lds, const bf16_t* H, unsigned char* MASKB, int bl, int qb) {
;     ...
;     for (int ks = 0; ks < nks; ++ks) {
;         const int kb = ks * 128 + wid * 16;
;         const bf16x8 ikf = ikn0; ikn0 = ikn1;
;         { const int kn = (ks + 2 < nks) ? ks + 2 : nks - 1; ikn1 = *(const bf16x8*)(ikp + (size_t)kn * 128 * NP1); }
;         float sc[2][4]; idx_scores(ikf, iq, iw, iql, sc);
;         const bool chk = (ks == nks - 1);
; #pragma unroll
;         for (int qt = 0; qt < 2; ++qt) {
;             const int tq = qt ? tq1 : tq0;
; #pragma unroll
;             for (int j = 0; j < 4; ++j) {
;                 const int key = kb + lg * 4 + j;
;                 const unsigned bin = mono_key(sc[qt][j]) >> 21;
;                 unsigned inc = (bin & 1u) ? 65536u : 1u;
;                 if (chk) inc = (key <= tq) ? inc : 0u;
;                 __hip_atomic_fetch_add(&H11[(qt * 16 + lr) * 1025 + (bin >> 1)], inc, __ATOMIC_RELAXED, __HIP_MEMORY_SCOPE_WORKGROUP);
;             }
;         }
;     }
.LBB0_443:
	s_waitcnt vmcnt(0)
	v_mfma_f32_16x16x32_bf16 v[98:101], v[94:97], v[66:69], 0
	v_mfma_f32_16x16x32_bf16 v[102:105], v[94:97], v[74:77], 0
	v_mfma_f32_16x16x32_bf16 v[98:101], v[94:97], v[70:73], v[98:101]
	v_mfma_f32_16x16x32_bf16 v[102:105], v[94:97], v[78:81], v[102:105]
	v_mfma_f32_16x16x32_bf16 v[106:109], v[94:97], v[2:5], 0
	v_mfma_f32_16x16x32_bf16 v[110:113], v[94:97], v[6:9], 0
	v_mfma_f32_16x16x32_bf16 v[114:117], v[94:97], v[10:13], 0
	v_mfma_f32_16x16x32_bf16 v[118:121], v[94:97], v[14:17], 0
	s_add_i32 s0, s13, 2
	v_mov_b64_e32 v[82:83], v[90:91]
	s_min_i32 s0, s0, s96
	v_mov_b64_e32 v[84:85], v[92:93]
	v_mad_i64_i32 v[90:91], s[0:1], s0, v207, v[178:179]
	global_load_dwordx4 v[90:93], v[90:91], off
	v_fma_f32 v98, v163, |v106|, v98
	v_fma_f32 v99, v163, |v107|, v99
	v_fma_f32 v100, v163, |v108|, v100
	v_fma_f32 v101, v163, |v109|, v101
	v_mfma_f32_16x16x32_bf16 v[106:109], v[94:97], v[18:21], 0
	v_fma_f32 v98, v162, |v110|, v98
	v_fma_f32 v99, v162, |v111|, v99
	v_fma_f32 v100, v162, |v112|, v100
	v_fma_f32 v101, v162, |v113|, v101
	v_mfma_f32_16x16x32_bf16 v[110:113], v[94:97], v[22:25], 0
	v_fma_f32 v98, v165, |v114|, v98
	v_fma_f32 v99, v165, |v115|, v99
	v_fma_f32 v100, v165, |v116|, v100
	v_fma_f32 v101, v165, |v117|, v101
	v_mfma_f32_16x16x32_bf16 v[114:117], v[94:97], v[26:29], 0
	v_fma_f32 v98, v164, |v118|, v98
	v_fma_f32 v99, v164, |v119|, v99
	v_fma_f32 v100, v164, |v120|, v100
	v_fma_f32 v101, v164, |v121|, v101
	v_mfma_f32_16x16x32_bf16 v[118:121], v[94:97], v[30:33], 0
	v_fma_f32 v98, v167, |v106|, v98
	v_fma_f32 v99, v167, |v107|, v99
	v_fma_f32 v100, v167, |v108|, v100
	v_fma_f32 v101, v167, |v109|, v101
	v_mfma_f32_16x16x32_bf16 v[106:109], v[94:97], v[62:65], 0
	v_fma_f32 v98, v166, |v110|, v98
	v_fma_f32 v99, v166, |v111|, v99
	v_fma_f32 v100, v166, |v112|, v100
	v_fma_f32 v101, v166, |v113|, v101
	v_mfma_f32_16x16x32_bf16 v[110:113], v[94:97], v[34:37], 0
	v_fma_f32 v98, v169, |v114|, v98
	v_fma_f32 v99, v169, |v115|, v99
	v_fma_f32 v100, v169, |v116|, v100
	v_fma_f32 v101, v169, |v117|, v101
	v_mfma_f32_16x16x32_bf16 v[114:117], v[94:97], v[38:41], 0
	v_fma_f32 v98, v168, |v118|, v98
	v_fma_f32 v99, v168, |v119|, v99
	v_fma_f32 v100, v168, |v120|, v100
	v_fma_f32 v101, v168, |v121|, v101
	v_mfma_f32_16x16x32_bf16 v[118:121], v[94:97], v[42:45], 0
	v_fma_f32 v102, v171, |v106|, v102
	v_fma_f32 v103, v171, |v107|, v103
	v_fma_f32 v104, v171, |v108|, v104
	v_fma_f32 v105, v171, |v109|, v105
	v_mfma_f32_16x16x32_bf16 v[106:109], v[94:97], v[46:49], 0
	v_fma_f32 v102, v170, |v110|, v102
	v_fma_f32 v103, v170, |v111|, v103
	v_fma_f32 v104, v170, |v112|, v104
	v_fma_f32 v105, v170, |v113|, v105
	v_mfma_f32_16x16x32_bf16 v[110:113], v[94:97], v[50:53], 0
	v_fma_f32 v102, v173, |v114|, v102
	v_fma_f32 v103, v173, |v115|, v103
	v_fma_f32 v104, v173, |v116|, v104
	v_fma_f32 v105, v173, |v117|, v105
	v_mfma_f32_16x16x32_bf16 v[114:117], v[94:97], v[54:57], 0
	v_fma_f32 v102, v172, |v118|, v102
	v_fma_f32 v103, v172, |v119|, v103
	v_fma_f32 v104, v172, |v120|, v104
	v_fma_f32 v105, v172, |v121|, v105
	v_mfma_f32_16x16x32_bf16 v[118:121], v[94:97], v[58:61], 0
	v_fma_f32 v102, v175, |v106|, v102
	v_fma_f32 v103, v175, |v107|, v103
	v_fma_f32 v104, v175, |v108|, v104
	v_fma_f32 v105, v175, |v109|, v105
	v_fma_f32 v102, v174, |v110|, v102
	v_fma_f32 v103, v174, |v111|, v103
	v_fma_f32 v104, v174, |v112|, v104
	v_fma_f32 v105, v174, |v113|, v105
	v_fma_f32 v102, v177, |v114|, v102
	v_fma_f32 v103, v177, |v115|, v103
	v_fma_f32 v104, v177, |v116|, v104
	v_fma_f32 v105, v177, |v117|, v105
	v_fma_f32 v102, v176, |v118|, v102
	v_fma_f32 v103, v176, |v119|, v103
	v_fma_f32 v104, v176, |v120|, v104
	v_fma_f32 v105, v176, |v121|, v105
	v_add_f32_e32 v98, 0, v98
	v_ashrrev_i32_e32 v122, 31, v98
	v_or_b32_e32 v122, 0x80000000, v122
	v_xor_b32_e32 v98, v122, v98
	v_and_b32_e32 v122, 0x200000, v98
	v_bfe_u32 v123, v98, 22, 10
	v_cmp_eq_u32_e32 vcc, 0, v122
	v_lshl_add_u32 v123, v123, 2, v0
	s_nop 0
	v_cndmask_b32_e64 v122, v208, 1, vcc
	ds_add_u32 v123, v122
	v_add_f32_e32 v99, 0, v99
	v_ashrrev_i32_e32 v124, 31, v99
	v_or_b32_e32 v124, 0x80000000, v124
	v_xor_b32_e32 v99, v124, v99
	v_and_b32_e32 v124, 0x200000, v99
	v_bfe_u32 v125, v99, 22, 10
	v_cmp_eq_u32_e32 vcc, 0, v124
	v_lshl_add_u32 v125, v125, 2, v0
	s_nop 0
	v_cndmask_b32_e64 v124, v208, 1, vcc
	ds_add_u32 v125, v124
	v_add_f32_e32 v100, 0, v100
	v_ashrrev_i32_e32 v180, 31, v100
	v_or_b32_e32 v180, 0x80000000, v180
	v_xor_b32_e32 v100, v180, v100
	v_and_b32_e32 v180, 0x200000, v100
	v_bfe_u32 v181, v100, 22, 10
	v_cmp_eq_u32_e32 vcc, 0, v180
	v_lshl_add_u32 v181, v181, 2, v0
	s_nop 0
	v_cndmask_b32_e64 v180, v208, 1, vcc
	ds_add_u32 v181, v180
	v_add_f32_e32 v101, 0, v101
	v_ashrrev_i32_e32 v182, 31, v101
	v_or_b32_e32 v182, 0x80000000, v182
	v_xor_b32_e32 v101, v182, v101
	v_and_b32_e32 v182, 0x200000, v101
	v_bfe_u32 v183, v101, 22, 10
	v_cmp_eq_u32_e32 vcc, 0, v182
	v_lshl_add_u32 v183, v183, 2, v0
	s_nop 0
	v_cndmask_b32_e64 v182, v208, 1, vcc
	ds_add_u32 v183, v182
	v_add_f32_e32 v102, 0, v102
	v_ashrrev_i32_e32 v184, 31, v102
	v_or_b32_e32 v184, 0x80000000, v184
	v_xor_b32_e32 v102, v184, v102
	v_and_b32_e32 v184, 0x200000, v102
	v_bfe_u32 v185, v102, 22, 10
	v_cmp_eq_u32_e32 vcc, 0, v184
	v_lshl_add_u32 v185, v185, 2, v224
	s_nop 0
	v_cndmask_b32_e64 v184, v208, 1, vcc
	ds_add_u32 v185, v184
	v_add_f32_e32 v103, 0, v103
	v_ashrrev_i32_e32 v186, 31, v103
	v_or_b32_e32 v186, 0x80000000, v186
	v_xor_b32_e32 v103, v186, v103
	v_and_b32_e32 v186, 0x200000, v103
	v_bfe_u32 v187, v103, 22, 10
	v_cmp_eq_u32_e32 vcc, 0, v186
	v_lshl_add_u32 v187, v187, 2, v224
	s_nop 0
	v_cndmask_b32_e64 v186, v208, 1, vcc
	ds_add_u32 v187, v186
	v_add_f32_e32 v104, 0, v104
	v_ashrrev_i32_e32 v188, 31, v104
	v_or_b32_e32 v188, 0x80000000, v188
	v_xor_b32_e32 v104, v188, v104
	v_and_b32_e32 v188, 0x200000, v104
	v_bfe_u32 v189, v104, 22, 10
	v_cmp_eq_u32_e32 vcc, 0, v188
	v_lshl_add_u32 v189, v189, 2, v224
	s_nop 0
	v_cndmask_b32_e64 v188, v208, 1, vcc
	ds_add_u32 v189, v188
	v_add_f32_e32 v105, 0, v105
	v_ashrrev_i32_e32 v190, 31, v105
	v_or_b32_e32 v190, 0x80000000, v190
	v_xor_b32_e32 v105, v190, v105
	v_and_b32_e32 v190, 0x200000, v105
	v_bfe_u32 v191, v105, 22, 10
	v_cmp_eq_u32_e32 vcc, 0, v190
	v_lshl_add_u32 v191, v191, 2, v224
	s_nop 0
	v_cndmask_b32_e64 v190, v208, 1, vcc
	ds_add_u32 v191, v190
	s_add_i32 s13, s13, 1
	s_cmp_eq_u32 s96, s13
	v_mov_b64_e32 v[96:97], v[84:85]
	v_mov_b64_e32 v[94:95], v[82:83]
	s_cbranch_scc0 .LBB0_443
	s_waitcnt vmcnt(0)
	v_add_u32_e32 v90, 0x10040, v223
	s_mov_b64 s[0:1], 0
